# v44: v42 + non-temporal hint on the NSA per-item gate loads (read once)
# baseline (speedup 1.0000x reference)
.LBB0_1234:
	v_readlane_b32 s4, v254, 13
	v_readlane_b32 s8, v254, 17
	v_readlane_b32 s9, v254, 18
	v_readlane_b32 s5, v254, 14
	s_movk_i32 s4, 0x60
	v_mov_b64_e32 v[68:69], s[8:9]
	v_mad_u64_u32 v[68:69], s[4:5], v112, s4, v[68:69]
	s_mul_i32 s4, s24, 48
	s_mov_b32 s5, s75
	v_lshl_add_u64 v[154:155], v[68:69], 0, s[4:5]
	global_load_dword v66, v[154:155], off nt
	global_load_dword v70, v[154:155], off offset:12 nt
	global_load_dword v72, v[154:155], off offset:24 nt
	global_load_dword v74, v[154:155], off offset:36 nt
	v_mov_b64_e32 v[68:69], s[88:89]
	s_lshl_b32 s74, s0, 1
	s_movk_i32 s0, 0x880
	v_mad_u64_u32 v[68:69], s[4:5], v112, s0, v[68:69]
	v_mov_b32_e32 v151, v0
	v_lshl_add_u64 v[68:69], v[68:69], 0, s[74:75]
	v_lshl_add_u64 v[152:153], v[68:69], 0, v[150:151]
	s_cmp_gt_u32 s1, 63
	v_readlane_b32 s6, v254, 15
	v_readlane_b32 s7, v254, 16
	v_readlane_b32 s10, v254, 19
	v_readlane_b32 s11, v254, 20
	v_readlane_b32 s12, v254, 21
	v_readlane_b32 s13, v254, 22
	v_readlane_b32 s14, v254, 23
	v_readlane_b32 s15, v254, 24
	v_readlane_b32 s16, v254, 25
	v_readlane_b32 s17, v254, 26
	v_readlane_b32 s18, v254, 27
	v_readlane_b32 s19, v254, 28
	s_waitcnt vmcnt(0)
	v_pk_mul_f32 v[26:27], v[26:27], v[66:67] op_sel_hi:[1,0]
	v_pk_mul_f32 v[28:29], v[28:29], v[66:67] op_sel_hi:[1,0]
	v_pk_mul_f32 v[62:63], v[62:63], v[66:67] op_sel_hi:[1,0]
	v_pk_mul_f32 v[64:65], v[64:65], v[66:67] op_sel_hi:[1,0]
	v_pk_mul_f32 v[58:59], v[58:59], v[66:67] op_sel_hi:[1,0]
	v_pk_mul_f32 v[60:61], v[60:61], v[66:67] op_sel_hi:[1,0]
	v_pk_mul_f32 v[54:55], v[54:55], v[66:67] op_sel_hi:[1,0]
	v_pk_mul_f32 v[56:57], v[56:57], v[66:67] op_sel_hi:[1,0]
	v_cvt_pk_bf16_f32 v26, v26, v27
	v_cvt_pk_bf16_f32 v27, v28, v29
	v_cvt_pk_bf16_f32 v28, v62, v63
	v_cvt_pk_bf16_f32 v29, v64, v65
	v_cvt_pk_bf16_f32 v58, v58, v59
	v_cvt_pk_bf16_f32 v59, v60, v61
	v_cvt_pk_bf16_f32 v54, v54, v55
	v_cvt_pk_bf16_f32 v55, v56, v57
	global_store_dwordx2 v[152:153], v[26:27], off
	global_store_dwordx2 v[152:153], v[28:29], off offset:32
	global_store_dwordx2 v[152:153], v[58:59], off offset:64
	global_store_dwordx2 v[152:153], v[54:55], off offset:96
	v_pk_mul_f32 v[28:29], v[50:51], v[70:71] op_sel_hi:[1,0]
	v_pk_mul_f32 v[50:51], v[52:53], v[70:71] op_sel_hi:[1,0]
	v_pk_mul_f32 v[46:47], v[46:47], v[70:71] op_sel_hi:[1,0]
	v_pk_mul_f32 v[48:49], v[48:49], v[70:71] op_sel_hi:[1,0]
	v_pk_mul_f32 v[42:43], v[42:43], v[70:71] op_sel_hi:[1,0]
	v_pk_mul_f32 v[44:45], v[44:45], v[70:71] op_sel_hi:[1,0]
	v_pk_mul_f32 v[38:39], v[38:39], v[70:71] op_sel_hi:[1,0]
	v_pk_mul_f32 v[26:27], v[40:41], v[70:71] op_sel_hi:[1,0]
	v_cvt_pk_bf16_f32 v28, v28, v29
	v_cvt_pk_bf16_f32 v29, v50, v51
	v_cvt_pk_bf16_f32 v40, v46, v47
	v_cvt_pk_bf16_f32 v41, v48, v49
	v_cvt_pk_bf16_f32 v42, v42, v43
	v_cvt_pk_bf16_f32 v43, v44, v45
	v_cvt_pk_bf16_f32 v38, v38, v39
	v_cvt_pk_bf16_f32 v39, v26, v27
	global_store_dwordx2 v[152:153], v[28:29], off offset:128
	global_store_dwordx2 v[152:153], v[40:41], off offset:160
	global_store_dwordx2 v[152:153], v[42:43], off offset:192
	global_store_dwordx2 v[152:153], v[38:39], off offset:224
	v_pk_mul_f32 v[28:29], v[34:35], v[72:73] op_sel_hi:[1,0]
	v_pk_mul_f32 v[34:35], v[36:37], v[72:73] op_sel_hi:[1,0]
	v_pk_mul_f32 v[30:31], v[30:31], v[72:73] op_sel_hi:[1,0]
	v_pk_mul_f32 v[32:33], v[32:33], v[72:73] op_sel_hi:[1,0]
	v_pk_mul_f32 v[22:23], v[22:23], v[72:73] op_sel_hi:[1,0]
	v_pk_mul_f32 v[24:25], v[24:25], v[72:73] op_sel_hi:[1,0]
	v_pk_mul_f32 v[18:19], v[18:19], v[72:73] op_sel_hi:[1,0]
	v_pk_mul_f32 v[20:21], v[20:21], v[72:73] op_sel_hi:[1,0]
	v_cvt_pk_bf16_f32 v26, v28, v29
	v_cvt_pk_bf16_f32 v27, v34, v35
	v_cvt_pk_bf16_f32 v28, v30, v31
	v_cvt_pk_bf16_f32 v29, v32, v33
	v_cvt_pk_bf16_f32 v22, v22, v23
	v_cvt_pk_bf16_f32 v23, v24, v25
	v_cvt_pk_bf16_f32 v18, v18, v19
	v_cvt_pk_bf16_f32 v19, v20, v21
	global_store_dwordx2 v[152:153], v[26:27], off offset:256
	global_store_dwordx2 v[152:153], v[28:29], off offset:288
	global_store_dwordx2 v[152:153], v[22:23], off offset:320
	global_store_dwordx2 v[152:153], v[18:19], off offset:352
	v_lshl_add_u32 v33, v67, 2, v172
	v_pk_mul_f32 v[14:15], v[14:15], v[74:75] op_sel_hi:[1,0]
	v_pk_mul_f32 v[16:17], v[16:17], v[74:75] op_sel_hi:[1,0]
	v_pk_mul_f32 v[10:11], v[10:11], v[74:75] op_sel_hi:[1,0]
	v_pk_mul_f32 v[12:13], v[12:13], v[74:75] op_sel_hi:[1,0]
	v_pk_mul_f32 v[6:7], v[6:7], v[74:75] op_sel_hi:[1,0]
	v_pk_mul_f32 v[8:9], v[8:9], v[74:75] op_sel_hi:[1,0]
	v_pk_mul_f32 v[2:3], v[2:3], v[74:75] op_sel_hi:[1,0]
	v_pk_mul_f32 v[4:5], v[4:5], v[74:75] op_sel_hi:[1,0]
	v_cvt_pk_bf16_f32 v14, v14, v15
	v_cvt_pk_bf16_f32 v15, v16, v17
	v_cvt_pk_bf16_f32 v10, v10, v11
	v_cvt_pk_bf16_f32 v11, v12, v13
	v_cvt_pk_bf16_f32 v6, v6, v7
	v_cvt_pk_bf16_f32 v7, v8, v9
	v_cvt_pk_bf16_f32 v2, v2, v3
	v_cvt_pk_bf16_f32 v3, v4, v5
	global_store_dwordx2 v[152:153], v[14:15], off offset:384
	global_store_dwordx2 v[152:153], v[10:11], off offset:416
	global_store_dwordx2 v[152:153], v[6:7], off offset:448
	global_store_dwordx2 v[152:153], v[2:3], off offset:480
	s_waitcnt lgkmcnt(0)
	ds_read_b32 v34, v33 offset:8192
	v_mov_b32_e32 v2, -1.0
	v_mov_b32_e32 v3, -1.0
	s_cbranch_scc0 .LBB0_1236
	ds_read_b32 v3, v33 offset:8196
	s_cmpk_lt_u32 s1, 0xc0
	s_cselect_b64 vcc, -1, 0
	v_cndmask_b32_e32 v4, 0, v181, vcc
	s_waitcnt lgkmcnt(0)
	v_add_f32_e32 v3, v4, v3

.LBB0_1307:
	v_lshl_add_u64 v[2:3], s[16:17], 2, v[154:155]
	global_load_dwordx2 v[80:81], v[152:153], off
	global_load_dwordx2 v[82:83], v[152:153], off offset:32
	global_load_dwordx2 v[84:85], v[152:153], off offset:64
	global_load_dwordx2 v[86:87], v[152:153], off offset:96
	global_load_dwordx2 v[88:89], v[152:153], off offset:128
	global_load_dwordx2 v[90:91], v[152:153], off offset:160
	global_load_dwordx2 v[92:93], v[152:153], off offset:192
	global_load_dwordx2 v[94:95], v[152:153], off offset:224
	global_load_dwordx2 v[96:97], v[152:153], off offset:256
	global_load_dwordx2 v[98:99], v[152:153], off offset:288
	global_load_dwordx2 v[100:101], v[152:153], off offset:320
	global_load_dwordx2 v[102:103], v[152:153], off offset:352
	global_load_dwordx2 v[104:105], v[152:153], off offset:384
	global_load_dwordx2 v[106:107], v[152:153], off offset:416
	global_load_dwordx2 v[108:109], v[152:153], off offset:448
	global_load_dwordx2 v[110:111], v[152:153], off offset:480
	global_load_dword v142, v[2:3], off
	global_load_dword v143, v[2:3], off offset:12
	global_load_dword v144, v[2:3], off offset:24
	global_load_dword v145, v[2:3], off offset:36
	s_andn2_b64 vcc, exec, s[14:15]
	s_cbranch_vccnz .Lnsa_epi_nog
	global_load_dwordx2 v[112:113], v[164:165], off nt
	global_load_dwordx2 v[114:115], v[164:165], off offset:32 nt
	global_load_dwordx2 v[116:117], v[164:165], off offset:64 nt
	global_load_dwordx2 v[118:119], v[164:165], off offset:96 nt
	global_load_dwordx2 v[120:121], v[164:165], off offset:128 nt
	global_load_dwordx2 v[122:123], v[164:165], off offset:160 nt
	global_load_dwordx2 v[124:125], v[164:165], off offset:192 nt
	global_load_dwordx2 v[126:127], v[164:165], off offset:224 nt
	global_load_dwordx2 v[128:129], v[164:165], off offset:256 nt
	global_load_dwordx2 v[130:131], v[164:165], off offset:288 nt
	global_load_dwordx2 v[132:133], v[164:165], off offset:320 nt
	global_load_dwordx2 v[134:135], v[164:165], off offset:352 nt
	global_load_dwordx2 v[136:137], v[164:165], off offset:384 nt
	global_load_dwordx2 v[138:139], v[164:165], off offset:416 nt
	global_load_dwordx2 v[140:141], v[164:165], off offset:448 nt
	global_load_dwordx2 v[146:147], v[164:165], off offset:480 nt
